# speedup vs baseline: 1.0147x; 1.0083x over previous
_Z8mega_fwd6Params:
	s_load_dwordx2 s[84:85], s[0:1], 0xe0
	s_add_u32 s12, s0, 0xe8
	v_and_b32_e32 v208, 0x3ff, v0
	v_readfirstlane_b32 s100, v0
	s_nop 1
	s_and_b32 s100, s100, 0x3ff
	s_cmpk_lt_u32 s100, 0x100
	s_cbranch_scc1 .Lprio0
	s_setprio 1
.Lprio0:
	s_addc_u32 s13, s1, 0
	v_cmp_eq_u32_e64 s[46:47], 0, v208
	s_and_saveexec_b64 s[14:15], s[46:47]
	s_nop 0
	v_writelane_b32 v254, s46, 0
	s_nop 1
	v_writelane_b32 v254, s47, 1
	s_cbranch_execz .LBB0_2
	s_load_dwordx16 s[68:83], s[0:1], 0x0
	s_load_dwordx8 s[4:11], s[0:1], 0xc0
	s_load_dwordx16 s[36:51], s[0:1], 0x80
	s_load_dwordx16 s[52:67], s[0:1], 0x40
	s_add_i32 s16, 0, 0x20000
	s_waitcnt lgkmcnt(0)
	v_mov_b32_e32 v2, s68
	v_mov_b32_e32 v3, s69
	v_mov_b32_e32 v4, s70
	v_mov_b32_e32 v5, s71
	v_mov_b32_e32 v1, s16
	s_add_i32 s16, 0, 0x20010
	ds_write_b128 v1, v[2:5]
	v_mov_b32_e32 v2, s72
	v_mov_b32_e32 v3, s73
	v_mov_b32_e32 v4, s74
	v_mov_b32_e32 v5, s75
	v_mov_b32_e32 v1, s16
	s_add_i32 s16, 0, 0x20020
	ds_write_b128 v1, v[2:5]
	v_mov_b32_e32 v2, s76
	v_mov_b32_e32 v3, s77
	v_mov_b32_e32 v4, s78
	v_mov_b32_e32 v5, s79
	v_mov_b32_e32 v1, s16
	s_add_i32 s16, 0, 0x20030
	ds_write_b128 v1, v[2:5]
	v_mov_b32_e32 v2, s80
	v_mov_b32_e32 v3, s81
	v_mov_b32_e32 v4, s82
	v_mov_b32_e32 v5, s83
	v_mov_b32_e32 v1, s16
	s_add_i32 s16, 0, 0x20040
	ds_write_b128 v1, v[2:5]
	v_mov_b32_e32 v2, s52
	v_mov_b32_e32 v3, s53
	v_mov_b32_e32 v4, s54
	v_mov_b32_e32 v5, s55
	v_mov_b32_e32 v1, s16
	s_add_i32 s16, 0, 0x20050
	ds_write_b128 v1, v[2:5]
	v_mov_b32_e32 v2, s56
	v_mov_b32_e32 v3, s57
	v_mov_b32_e32 v4, s58
	v_mov_b32_e32 v5, s59
	v_mov_b32_e32 v1, s16
	s_add_i32 s16, 0, 0x20060
	ds_write_b128 v1, v[2:5]
	v_mov_b32_e32 v2, s60
	v_mov_b32_e32 v3, s61
	v_mov_b32_e32 v4, s62
	v_mov_b32_e32 v5, s63
	v_mov_b32_e32 v1, s16
	s_add_i32 s16, 0, 0x20070
	ds_write_b128 v1, v[2:5]
	v_mov_b32_e32 v2, s64
	v_mov_b32_e32 v3, s65
	v_mov_b32_e32 v4, s66
	v_mov_b32_e32 v5, s67
	v_mov_b32_e32 v1, s16
	s_add_i32 s16, 0, 0x20080
	ds_write_b128 v1, v[2:5]
	v_mov_b32_e32 v2, s36
	v_mov_b32_e32 v3, s37
	v_mov_b32_e32 v4, s38
	v_mov_b32_e32 v5, s39
	v_mov_b32_e32 v1, s16
	s_add_i32 s16, 0, 0x20090
	ds_write_b128 v1, v[2:5]
	v_mov_b32_e32 v2, s40
	v_mov_b32_e32 v3, s41
	v_mov_b32_e32 v4, s42
	v_mov_b32_e32 v5, s43
	v_mov_b32_e32 v1, s16
	s_add_i32 s16, 0, 0x200a0
	ds_write_b128 v1, v[2:5]
	v_mov_b32_e32 v2, s44
	v_mov_b32_e32 v3, s45
	v_mov_b32_e32 v4, s46
	v_mov_b32_e32 v5, s47
	v_mov_b32_e32 v1, s16
	s_add_i32 s16, 0, 0x200b0
	ds_write_b128 v1, v[2:5]
	v_mov_b32_e32 v2, s48
	v_mov_b32_e32 v3, s49
	v_mov_b32_e32 v4, s50
	v_mov_b32_e32 v5, s51
	v_mov_b32_e32 v1, s16
	ds_write_b128 v1, v[2:5]
	v_mov_b32_e32 v2, s4
	s_add_i32 s4, 0, 0x200c0
	v_mov_b32_e32 v3, s5
	v_mov_b32_e32 v4, s6
	v_mov_b32_e32 v5, s7
	v_mov_b32_e32 v1, s4
	s_add_i32 s4, 0, 0x200d0
	v_readlane_b32 s46, v254, 0
	ds_write_b128 v1, v[2:5]
	v_mov_b32_e32 v2, s8
	v_mov_b32_e32 v3, s9
	v_mov_b32_e32 v4, s10
	v_mov_b32_e32 v5, s11
	v_mov_b32_e32 v1, s4
	s_add_i32 s4, 0, 0x200e0
	v_readlane_b32 s47, v254, 1
	ds_write_b128 v1, v[2:5]
	v_mov_b32_e32 v1, s4
	v_mov_b64_e32 v[2:3], s[84:85]
	ds_write_b64 v1, v[2:3]

.LBB0_184:
	ds_read_b128 v[164:167], v161
	ds_read_b128 v[168:171], v161 offset:1024
	ds_read_b128 v[176:179], v161 offset:2048
	ds_read_b128 v[180:183], v161 offset:3072
	v_add_u32_e32 v162, 0xc000, v147
	v_lshl_add_u64 v[172:173], v[134:135], 0, s[10:11]
	v_readfirstlane_b32 s2, v162
	v_add_u32_e32 v163, 0xe000, v147
	v_lshl_add_u64 v[230:231], v[172:173], 0, s[60:61]
	s_mov_b32 m0, s2
	v_lshl_add_u64 v[246:247], v[132:133], 0, s[10:11]
	v_readfirstlane_b32 s2, v163
	ds_read_b128 v[184:187], v143
	ds_read_b128 v[188:191], v143 offset:1024
	ds_read_b128 v[192:195], v142
	ds_read_b128 v[196:199], v142 offset:1024
	ds_read_b128 v[200:203], v141
	ds_read_b128 v[204:207], v141 offset:1024
	ds_read_b128 v[222:225], v140
	ds_read_b128 v[226:229], v140 offset:1024
	global_load_lds_dwordx4 v[230:231], off
	v_lshl_add_u64 v[230:231], v[246:247], 0, s[60:61]
	s_mov_b32 m0, s2
	s_nop 0
	global_load_lds_dwordx4 v[230:231], off
	s_waitcnt lgkmcnt(8)
	s_barrier
	s_waitcnt lgkmcnt(0)
	s_waitcnt lgkmcnt(0)
	v_mfma_f32_16x16x32_bf16 v[126:129], v[184:187], v[164:167], v[126:129]
	v_mfma_f32_16x16x32_bf16 v[122:125], v[184:187], v[176:179], v[122:125]
	v_mfma_f32_16x16x32_bf16 v[118:121], v[192:195], v[164:167], v[118:121]
	v_mfma_f32_16x16x32_bf16 v[114:117], v[192:195], v[176:179], v[114:117]
	v_mfma_f32_16x16x32_bf16 v[110:113], v[200:203], v[164:167], v[110:113]
	v_mfma_f32_16x16x32_bf16 v[106:109], v[200:203], v[176:179], v[106:109]
	v_mfma_f32_16x16x32_bf16 v[102:105], v[222:225], v[164:167], v[102:105]
	v_mfma_f32_16x16x32_bf16 v[98:101], v[222:225], v[176:179], v[98:101]
	v_mfma_f32_16x16x32_bf16 v[126:129], v[188:191], v[168:171], v[126:129]
	v_mfma_f32_16x16x32_bf16 v[122:125], v[188:191], v[180:183], v[122:125]
	v_mfma_f32_16x16x32_bf16 v[118:121], v[196:199], v[168:171], v[118:121]
	v_mfma_f32_16x16x32_bf16 v[114:117], v[196:199], v[180:183], v[114:117]
	v_mfma_f32_16x16x32_bf16 v[110:113], v[204:207], v[168:171], v[110:113]
	v_mfma_f32_16x16x32_bf16 v[106:109], v[204:207], v[180:183], v[106:109]
	v_mfma_f32_16x16x32_bf16 v[102:105], v[226:229], v[168:171], v[102:105]
	v_mfma_f32_16x16x32_bf16 v[98:101], v[226:229], v[180:183], v[98:101]
	s_barrier
	v_lshl_add_u64 v[248:249], v[138:139], 0, s[10:11]
	v_readfirstlane_b32 s2, v144
	v_lshl_add_u64 v[250:251], v[248:249], 0, s[62:63]
	s_mov_b32 m0, s2
	ds_read_b128 v[230:233], v160
	ds_read_b128 v[234:237], v160 offset:1024
	ds_read_b128 v[238:241], v160 offset:2048
	ds_read_b128 v[242:245], v160 offset:3072
	global_load_lds_dwordx4 v[250:251], off
	v_lshl_add_u64 v[250:251], v[136:137], 0, s[10:11]
	v_readfirstlane_b32 s2, v146
	v_lshl_add_u64 v[252:253], v[250:251], 0, s[62:63]
	s_mov_b32 m0, s2
	s_nop 0
	global_load_lds_dwordx4 v[252:253], off
	s_barrier
	s_waitcnt lgkmcnt(0)
	s_waitcnt lgkmcnt(0)
	v_mfma_f32_16x16x32_bf16 v[92:95], v[184:187], v[230:233], v[92:95]
	v_mfma_f32_16x16x32_bf16 v[88:91], v[184:187], v[238:241], v[88:91]
	v_mfma_f32_16x16x32_bf16 v[84:87], v[192:195], v[230:233], v[84:87]
	v_mfma_f32_16x16x32_bf16 v[80:83], v[192:195], v[238:241], v[80:83]
	v_mfma_f32_16x16x32_bf16 v[76:79], v[200:203], v[230:233], v[76:79]
	v_mfma_f32_16x16x32_bf16 v[72:75], v[200:203], v[238:241], v[72:75]
	v_mfma_f32_16x16x32_bf16 v[68:71], v[222:225], v[230:233], v[68:71]
	v_mfma_f32_16x16x32_bf16 v[64:67], v[222:225], v[238:241], v[64:67]
	v_mfma_f32_16x16x32_bf16 v[92:95], v[188:191], v[234:237], v[92:95]
	v_mfma_f32_16x16x32_bf16 v[88:91], v[188:191], v[242:245], v[88:91]
	v_mfma_f32_16x16x32_bf16 v[84:87], v[196:199], v[234:237], v[84:87]
	v_mfma_f32_16x16x32_bf16 v[80:83], v[196:199], v[242:245], v[80:83]
	v_mfma_f32_16x16x32_bf16 v[76:79], v[204:207], v[234:237], v[76:79]
	v_mfma_f32_16x16x32_bf16 v[72:75], v[204:207], v[242:245], v[72:75]
	v_mfma_f32_16x16x32_bf16 v[68:71], v[226:229], v[234:237], v[68:71]
	v_mfma_f32_16x16x32_bf16 v[64:67], v[226:229], v[242:245], v[64:67]
	v_readfirstlane_b32 s2, v147
	v_lshl_add_u64 v[252:253], v[172:173], 0, s[62:63]
	s_mov_b32 m0, s2
	v_readfirstlane_b32 s2, v148
	s_barrier
	ds_read_b128 v[184:187], v143 offset:16384
	ds_read_b128 v[188:191], v143 offset:17408
	ds_read_b128 v[192:195], v142 offset:16384
	ds_read_b128 v[196:199], v142 offset:17408
	ds_read_b128 v[200:203], v141 offset:16384
	ds_read_b128 v[204:207], v141 offset:17408
	ds_read_b128 v[222:225], v140 offset:16384
	ds_read_b128 v[226:229], v140 offset:17408
	global_load_lds_dwordx4 v[252:253], off
	v_lshl_add_u64 v[252:253], v[246:247], 0, s[62:63]
	s_mov_b32 m0, s2
	s_nop 0
	global_load_lds_dwordx4 v[252:253], off
	s_barrier
	s_waitcnt lgkmcnt(0)
	s_waitcnt lgkmcnt(0)
	v_mfma_f32_16x16x32_bf16 v[60:63], v[184:187], v[164:167], v[60:63]
	v_mfma_f32_16x16x32_bf16 v[56:59], v[184:187], v[176:179], v[56:59]
	v_mfma_f32_16x16x32_bf16 v[52:55], v[192:195], v[164:167], v[52:55]
	v_mfma_f32_16x16x32_bf16 v[48:51], v[192:195], v[176:179], v[48:51]
	v_mfma_f32_16x16x32_bf16 v[44:47], v[200:203], v[164:167], v[44:47]
	v_mfma_f32_16x16x32_bf16 v[40:43], v[200:203], v[176:179], v[40:43]
	v_mfma_f32_16x16x32_bf16 v[36:39], v[222:225], v[164:167], v[36:39]
	v_mfma_f32_16x16x32_bf16 v[32:35], v[222:225], v[176:179], v[32:35]
	v_mfma_f32_16x16x32_bf16 v[60:63], v[188:191], v[168:171], v[60:63]
	v_mfma_f32_16x16x32_bf16 v[56:59], v[188:191], v[180:183], v[56:59]
	v_mfma_f32_16x16x32_bf16 v[52:55], v[196:199], v[168:171], v[52:55]
	v_mfma_f32_16x16x32_bf16 v[48:51], v[196:199], v[180:183], v[48:51]
	v_mfma_f32_16x16x32_bf16 v[44:47], v[204:207], v[168:171], v[44:47]
	v_mfma_f32_16x16x32_bf16 v[40:43], v[204:207], v[180:183], v[40:43]
	v_mfma_f32_16x16x32_bf16 v[36:39], v[226:229], v[168:171], v[36:39]
	v_mfma_f32_16x16x32_bf16 v[32:35], v[226:229], v[180:183], v[32:35]
	s_barrier
	v_readfirstlane_b32 s2, v149
	v_lshl_add_u64 v[164:165], v[248:249], 0, s[64:65]
	s_mov_b32 m0, s2
	v_readfirstlane_b32 s2, v150
	global_load_lds_dwordx4 v[164:165], off
	v_lshl_add_u64 v[164:165], v[250:251], 0, s[64:65]
	s_mov_b32 m0, s2
	s_nop 0
	global_load_lds_dwordx4 v[164:165], off
	s_waitcnt vmcnt(6)
	s_barrier
	v_mfma_f32_16x16x32_bf16 v[28:31], v[184:187], v[230:233], v[28:31]
	v_mfma_f32_16x16x32_bf16 v[24:27], v[184:187], v[238:241], v[24:27]
	v_mfma_f32_16x16x32_bf16 v[20:23], v[192:195], v[230:233], v[20:23]
	v_mfma_f32_16x16x32_bf16 v[16:19], v[192:195], v[238:241], v[16:19]
	v_mfma_f32_16x16x32_bf16 v[12:15], v[200:203], v[230:233], v[12:15]
	v_mfma_f32_16x16x32_bf16 v[8:11], v[200:203], v[238:241], v[8:11]
	v_mfma_f32_16x16x32_bf16 v[4:7], v[222:225], v[230:233], v[4:7]
	v_mfma_f32_16x16x32_bf16 v[0:3], v[222:225], v[238:241], v[0:3]
	v_mfma_f32_16x16x32_bf16 v[28:31], v[188:191], v[234:237], v[28:31]
	v_mfma_f32_16x16x32_bf16 v[24:27], v[188:191], v[242:245], v[24:27]
	v_mfma_f32_16x16x32_bf16 v[20:23], v[196:199], v[234:237], v[20:23]
	v_mfma_f32_16x16x32_bf16 v[16:19], v[196:199], v[242:245], v[16:19]
	v_mfma_f32_16x16x32_bf16 v[12:15], v[204:207], v[234:237], v[12:15]
	v_mfma_f32_16x16x32_bf16 v[8:11], v[204:207], v[242:245], v[8:11]
	v_mfma_f32_16x16x32_bf16 v[4:7], v[226:229], v[234:237], v[4:7]
	v_mfma_f32_16x16x32_bf16 v[0:3], v[226:229], v[242:245], v[0:3]
	s_barrier
	ds_read_b128 v[164:167], v151
	ds_read_b128 v[168:171], v151 offset:1024
	ds_read_b128 v[176:179], v151 offset:2048
	ds_read_b128 v[180:183], v151 offset:3072
	v_readfirstlane_b32 s2, v152
	v_lshl_add_u64 v[230:231], v[172:173], 0, s[64:65]
	s_mov_b32 m0, s2
	v_readfirstlane_b32 s2, v153
	ds_read_b128 v[184:187], v143 offset:32768
	ds_read_b128 v[188:191], v143 offset:33792
	ds_read_b128 v[192:195], v142 offset:32768
	ds_read_b128 v[196:199], v142 offset:33792
	ds_read_b128 v[200:203], v141 offset:32768
	ds_read_b128 v[204:207], v141 offset:33792
	ds_read_b128 v[222:225], v140 offset:32768
	ds_read_b128 v[226:229], v140 offset:33792
	global_load_lds_dwordx4 v[230:231], off
	v_lshl_add_u64 v[230:231], v[246:247], 0, s[64:65]
	s_mov_b32 m0, s2
	s_nop 0
	global_load_lds_dwordx4 v[230:231], off
	s_waitcnt lgkmcnt(8)
	s_barrier
	s_waitcnt lgkmcnt(0)
	s_waitcnt lgkmcnt(0)
	v_mfma_f32_16x16x32_bf16 v[126:129], v[184:187], v[164:167], v[126:129]
	v_mfma_f32_16x16x32_bf16 v[122:125], v[184:187], v[176:179], v[122:125]
	v_mfma_f32_16x16x32_bf16 v[118:121], v[192:195], v[164:167], v[118:121]
	v_mfma_f32_16x16x32_bf16 v[114:117], v[192:195], v[176:179], v[114:117]
	v_mfma_f32_16x16x32_bf16 v[110:113], v[200:203], v[164:167], v[110:113]
	v_mfma_f32_16x16x32_bf16 v[106:109], v[200:203], v[176:179], v[106:109]
	v_mfma_f32_16x16x32_bf16 v[102:105], v[222:225], v[164:167], v[102:105]
	v_mfma_f32_16x16x32_bf16 v[98:101], v[222:225], v[176:179], v[98:101]
	v_mfma_f32_16x16x32_bf16 v[126:129], v[188:191], v[168:171], v[126:129]
	v_mfma_f32_16x16x32_bf16 v[122:125], v[188:191], v[180:183], v[122:125]
	v_mfma_f32_16x16x32_bf16 v[118:121], v[196:199], v[168:171], v[118:121]
	v_mfma_f32_16x16x32_bf16 v[114:117], v[196:199], v[180:183], v[114:117]
	v_mfma_f32_16x16x32_bf16 v[110:113], v[204:207], v[168:171], v[110:113]
	v_mfma_f32_16x16x32_bf16 v[106:109], v[204:207], v[180:183], v[106:109]
	v_mfma_f32_16x16x32_bf16 v[102:105], v[226:229], v[168:171], v[102:105]
	v_mfma_f32_16x16x32_bf16 v[98:101], v[226:229], v[180:183], v[98:101]
	s_barrier
	v_readfirstlane_b32 s2, v154
	v_lshl_add_u64 v[252:253], v[248:249], 0, s[66:67]
	s_mov_b32 m0, s2
	v_readfirstlane_b32 s2, v155
	ds_read_b128 v[230:233], v145
	ds_read_b128 v[234:237], v145 offset:1024
	ds_read_b128 v[238:241], v145 offset:2048
	ds_read_b128 v[242:245], v145 offset:3072
	global_load_lds_dwordx4 v[252:253], off
	v_lshl_add_u64 v[252:253], v[250:251], 0, s[66:67]
	s_mov_b32 m0, s2
	s_nop 0
	global_load_lds_dwordx4 v[252:253], off
	s_barrier
	s_waitcnt lgkmcnt(0)
	s_waitcnt lgkmcnt(0)
	v_mfma_f32_16x16x32_bf16 v[92:95], v[184:187], v[230:233], v[92:95]
	v_mfma_f32_16x16x32_bf16 v[88:91], v[184:187], v[238:241], v[88:91]
	v_mfma_f32_16x16x32_bf16 v[84:87], v[192:195], v[230:233], v[84:87]
	v_mfma_f32_16x16x32_bf16 v[80:83], v[192:195], v[238:241], v[80:83]
	v_mfma_f32_16x16x32_bf16 v[76:79], v[200:203], v[230:233], v[76:79]
	v_mfma_f32_16x16x32_bf16 v[72:75], v[200:203], v[238:241], v[72:75]
	v_mfma_f32_16x16x32_bf16 v[68:71], v[222:225], v[230:233], v[68:71]
	v_mfma_f32_16x16x32_bf16 v[64:67], v[222:225], v[238:241], v[64:67]
	v_mfma_f32_16x16x32_bf16 v[92:95], v[188:191], v[234:237], v[92:95]
	v_mfma_f32_16x16x32_bf16 v[88:91], v[188:191], v[242:245], v[88:91]
	v_mfma_f32_16x16x32_bf16 v[84:87], v[196:199], v[234:237], v[84:87]
	v_mfma_f32_16x16x32_bf16 v[80:83], v[196:199], v[242:245], v[80:83]
	v_mfma_f32_16x16x32_bf16 v[76:79], v[204:207], v[234:237], v[76:79]
	v_mfma_f32_16x16x32_bf16 v[72:75], v[204:207], v[242:245], v[72:75]
	v_mfma_f32_16x16x32_bf16 v[68:71], v[226:229], v[234:237], v[68:71]
	v_mfma_f32_16x16x32_bf16 v[64:67], v[226:229], v[242:245], v[64:67]
	v_readfirstlane_b32 s2, v156
	v_lshl_add_u64 v[172:173], v[172:173], 0, s[66:67]
	s_mov_b32 m0, s2
	v_readfirstlane_b32 s2, v157
	s_barrier
	ds_read_b128 v[184:187], v143 offset:49152
	ds_read_b128 v[188:191], v143 offset:50176
	ds_read_b128 v[192:195], v142 offset:49152
	ds_read_b128 v[196:199], v142 offset:50176
	ds_read_b128 v[200:203], v141 offset:49152
	ds_read_b128 v[204:207], v141 offset:50176
	ds_read_b128 v[222:225], v140 offset:49152
	ds_read_b128 v[226:229], v140 offset:50176
	global_load_lds_dwordx4 v[172:173], off
	v_lshl_add_u64 v[172:173], v[246:247], 0, s[66:67]
	s_mov_b32 m0, s2
	s_nop 0
	global_load_lds_dwordx4 v[172:173], off
	s_barrier
	s_waitcnt lgkmcnt(0)
	s_waitcnt lgkmcnt(0)
	v_mfma_f32_16x16x32_bf16 v[60:63], v[184:187], v[164:167], v[60:63]
	v_mfma_f32_16x16x32_bf16 v[56:59], v[184:187], v[176:179], v[56:59]
	v_mfma_f32_16x16x32_bf16 v[52:55], v[192:195], v[164:167], v[52:55]
	v_mfma_f32_16x16x32_bf16 v[48:51], v[192:195], v[176:179], v[48:51]
	v_mfma_f32_16x16x32_bf16 v[44:47], v[200:203], v[164:167], v[44:47]
	v_mfma_f32_16x16x32_bf16 v[40:43], v[200:203], v[176:179], v[40:43]
	v_mfma_f32_16x16x32_bf16 v[36:39], v[222:225], v[164:167], v[36:39]
	v_mfma_f32_16x16x32_bf16 v[32:35], v[222:225], v[176:179], v[32:35]
	v_mfma_f32_16x16x32_bf16 v[60:63], v[188:191], v[168:171], v[60:63]
	v_mfma_f32_16x16x32_bf16 v[56:59], v[188:191], v[180:183], v[56:59]
	v_mfma_f32_16x16x32_bf16 v[52:55], v[196:199], v[168:171], v[52:55]
	v_mfma_f32_16x16x32_bf16 v[48:51], v[196:199], v[180:183], v[48:51]
	v_mfma_f32_16x16x32_bf16 v[44:47], v[204:207], v[168:171], v[44:47]
	v_mfma_f32_16x16x32_bf16 v[40:43], v[204:207], v[180:183], v[40:43]
	v_mfma_f32_16x16x32_bf16 v[36:39], v[226:229], v[168:171], v[36:39]
	v_mfma_f32_16x16x32_bf16 v[32:35], v[226:229], v[180:183], v[32:35]
	s_barrier
	v_readfirstlane_b32 s2, v158
	v_lshl_add_u64 v[164:165], v[248:249], 0, s[68:69]
	s_mov_b32 m0, s2
	v_readfirstlane_b32 s2, v159
	global_load_lds_dwordx4 v[164:165], off
	v_lshl_add_u64 v[164:165], v[250:251], 0, s[68:69]
	s_mov_b32 m0, s2
	s_nop 0
	global_load_lds_dwordx4 v[164:165], off
	s_waitcnt vmcnt(6)
	s_barrier
	v_mfma_f32_16x16x32_bf16 v[28:31], v[184:187], v[230:233], v[28:31]
	v_mfma_f32_16x16x32_bf16 v[24:27], v[184:187], v[238:241], v[24:27]
	v_mfma_f32_16x16x32_bf16 v[20:23], v[192:195], v[230:233], v[20:23]
	v_mfma_f32_16x16x32_bf16 v[16:19], v[192:195], v[238:241], v[16:19]
	v_mfma_f32_16x16x32_bf16 v[12:15], v[200:203], v[230:233], v[12:15]
	v_mfma_f32_16x16x32_bf16 v[8:11], v[200:203], v[238:241], v[8:11]
	v_mfma_f32_16x16x32_bf16 v[4:7], v[222:225], v[230:233], v[4:7]
	v_mfma_f32_16x16x32_bf16 v[0:3], v[222:225], v[238:241], v[0:3]
	v_mfma_f32_16x16x32_bf16 v[28:31], v[188:191], v[234:237], v[28:31]
	v_mfma_f32_16x16x32_bf16 v[24:27], v[188:191], v[242:245], v[24:27]
	v_mfma_f32_16x16x32_bf16 v[20:23], v[196:199], v[234:237], v[20:23]
	v_mfma_f32_16x16x32_bf16 v[16:19], v[196:199], v[242:245], v[16:19]
	v_mfma_f32_16x16x32_bf16 v[12:15], v[204:207], v[234:237], v[12:15]
	v_mfma_f32_16x16x32_bf16 v[8:11], v[204:207], v[242:245], v[8:11]
	v_mfma_f32_16x16x32_bf16 v[4:7], v[226:229], v[234:237], v[4:7]
	v_mfma_f32_16x16x32_bf16 v[0:3], v[226:229], v[242:245], v[0:3]
	s_add_i32 s5, s5, 2
	s_add_u32 s10, s10, 0x100
	s_addc_u32 s11, s11, 0
	s_cmp_lt_u32 s5, 28
	s_barrier
	s_cbranch_scc1 .LBB0_184
	s_add_u32 s8, s8, 0x80f80
	s_addc_u32 s9, s9, 0
	v_readfirstlane_b32 s2, v162
	v_lshl_add_u64 v[172:173], s[8:9], 0, v[174:175]
	s_mov_b32 m0, s2
	v_readfirstlane_b32 s2, v163
	ds_read_b128 v[132:135], v161
	ds_read_b128 v[136:139], v161 offset:1024
	ds_read_b128 v[146:149], v161 offset:2048
	ds_read_b128 v[152:155], v161 offset:3072
	ds_read_b128 v[156:159], v143
	ds_read_b128 v[164:167], v143 offset:1024
	ds_read_b128 v[168:171], v142
	ds_read_b128 v[176:179], v142 offset:1024
	ds_read_b128 v[180:183], v141
	ds_read_b128 v[184:187], v141 offset:1024
	ds_read_b128 v[188:191], v140
	ds_read_b128 v[192:195], v140 offset:1024
	global_load_lds_dwordx4 v[172:173], off
	v_lshl_add_u64 v[130:131], s[8:9], 0, v[130:131]
	s_mov_b32 m0, s2
	s_nop 0
	global_load_lds_dwordx4 v[130:131], off
	s_barrier
	s_waitcnt lgkmcnt(0)
	s_waitcnt lgkmcnt(0)
	v_mfma_f32_16x16x32_bf16 v[126:129], v[156:159], v[132:135], v[126:129]
	v_mfma_f32_16x16x32_bf16 v[122:125], v[156:159], v[146:149], v[122:125]
	v_mfma_f32_16x16x32_bf16 v[118:121], v[168:171], v[132:135], v[118:121]
	v_mfma_f32_16x16x32_bf16 v[114:117], v[168:171], v[146:149], v[114:117]
	v_mfma_f32_16x16x32_bf16 v[110:113], v[180:183], v[132:135], v[110:113]
	v_mfma_f32_16x16x32_bf16 v[106:109], v[180:183], v[146:149], v[106:109]
	v_mfma_f32_16x16x32_bf16 v[102:105], v[188:191], v[132:135], v[102:105]
	v_mfma_f32_16x16x32_bf16 v[126:129], v[164:167], v[136:139], v[126:129]
	v_mfma_f32_16x16x32_bf16 v[122:125], v[164:167], v[152:155], v[122:125]
	v_mfma_f32_16x16x32_bf16 v[118:121], v[176:179], v[136:139], v[118:121]
	v_mfma_f32_16x16x32_bf16 v[114:117], v[176:179], v[152:155], v[114:117]
	v_mfma_f32_16x16x32_bf16 v[110:113], v[184:187], v[136:139], v[110:113]
	v_mfma_f32_16x16x32_bf16 v[106:109], v[184:187], v[152:155], v[106:109]
	v_mfma_f32_16x16x32_bf16 v[102:105], v[192:195], v[136:139], v[102:105]
	v_mfma_f32_16x16x32_bf16 v[98:101], v[188:191], v[146:149], v[98:101]
	v_mfma_f32_16x16x32_bf16 v[196:199], v[192:195], v[152:155], v[98:101]
	s_barrier
	s_nop 4
	ds_read_b128 v[98:101], v160
	ds_read_b128 v[200:203], v160 offset:1024
	ds_read_b128 v[204:207], v160 offset:2048
	ds_read_b128 v[160:163], v160 offset:3072
	s_barrier
	s_waitcnt lgkmcnt(0)
	s_waitcnt lgkmcnt(0)
	v_mfma_f32_16x16x32_bf16 v[92:95], v[156:159], v[98:101], v[92:95]
	v_mfma_f32_16x16x32_bf16 v[88:91], v[156:159], v[204:207], v[88:91]
	v_mfma_f32_16x16x32_bf16 v[84:87], v[168:171], v[98:101], v[84:87]
	v_mfma_f32_16x16x32_bf16 v[80:83], v[168:171], v[204:207], v[80:83]
	v_mfma_f32_16x16x32_bf16 v[76:79], v[180:183], v[98:101], v[76:79]
	v_mfma_f32_16x16x32_bf16 v[72:75], v[180:183], v[204:207], v[72:75]
	v_mfma_f32_16x16x32_bf16 v[68:71], v[188:191], v[98:101], v[68:71]
	v_mfma_f32_16x16x32_bf16 v[64:67], v[188:191], v[204:207], v[64:67]
	v_mfma_f32_16x16x32_bf16 v[222:225], v[164:167], v[200:203], v[92:95]
	v_mfma_f32_16x16x32_bf16 v[156:159], v[164:167], v[160:163], v[88:91]
	v_mfma_f32_16x16x32_bf16 v[164:167], v[176:179], v[200:203], v[84:87]
	v_mfma_f32_16x16x32_bf16 v[168:171], v[176:179], v[160:163], v[80:83]
	v_mfma_f32_16x16x32_bf16 v[176:179], v[184:187], v[200:203], v[76:79]
	v_mfma_f32_16x16x32_bf16 v[180:183], v[184:187], v[160:163], v[72:75]
	v_mfma_f32_16x16x32_bf16 v[184:187], v[192:195], v[200:203], v[68:71]
	v_mfma_f32_16x16x32_bf16 v[64:67], v[192:195], v[160:163], v[64:67]
	s_barrier
	ds_read_b128 v[68:71], v143 offset:16384
	ds_read_b128 v[72:75], v143 offset:17408
	ds_read_b128 v[76:79], v142 offset:16384
	ds_read_b128 v[80:83], v142 offset:17408
	ds_read_b128 v[84:87], v141 offset:16384
	ds_read_b128 v[88:91], v141 offset:17408
	ds_read_b128 v[92:95], v140 offset:16384
	ds_read_b128 v[188:191], v140 offset:17408
	s_waitcnt vmcnt(4)
	s_barrier
	s_waitcnt lgkmcnt(0)
	s_waitcnt lgkmcnt(0)
	v_mfma_f32_16x16x32_bf16 v[60:63], v[68:71], v[132:135], v[60:63]
	v_mfma_f32_16x16x32_bf16 v[56:59], v[68:71], v[146:149], v[56:59]
	v_mfma_f32_16x16x32_bf16 v[52:55], v[76:79], v[132:135], v[52:55]
	v_mfma_f32_16x16x32_bf16 v[48:51], v[76:79], v[146:149], v[48:51]
	v_mfma_f32_16x16x32_bf16 v[44:47], v[84:87], v[132:135], v[44:47]
	v_mfma_f32_16x16x32_bf16 v[40:43], v[84:87], v[146:149], v[40:43]
	v_mfma_f32_16x16x32_bf16 v[36:39], v[92:95], v[132:135], v[36:39]
	v_mfma_f32_16x16x32_bf16 v[32:35], v[92:95], v[146:149], v[32:35]
	v_mfma_f32_16x16x32_bf16 v[60:63], v[72:75], v[136:139], v[60:63]
	v_mfma_f32_16x16x32_bf16 v[56:59], v[72:75], v[152:155], v[56:59]
	v_mfma_f32_16x16x32_bf16 v[52:55], v[80:83], v[136:139], v[52:55]
	v_mfma_f32_16x16x32_bf16 v[48:51], v[80:83], v[152:155], v[48:51]
	v_mfma_f32_16x16x32_bf16 v[44:47], v[88:91], v[136:139], v[44:47]
	v_mfma_f32_16x16x32_bf16 v[40:43], v[88:91], v[152:155], v[40:43]
	v_mfma_f32_16x16x32_bf16 v[36:39], v[188:191], v[136:139], v[36:39]
	v_mfma_f32_16x16x32_bf16 v[32:35], v[188:191], v[152:155], v[32:35]
	v_mfma_f32_16x16x32_bf16 v[28:31], v[68:71], v[98:101], v[28:31]
	v_mfma_f32_16x16x32_bf16 v[24:27], v[68:71], v[204:207], v[24:27]
	v_mfma_f32_16x16x32_bf16 v[20:23], v[76:79], v[98:101], v[20:23]
	v_mfma_f32_16x16x32_bf16 v[16:19], v[76:79], v[204:207], v[16:19]
	v_mfma_f32_16x16x32_bf16 v[12:15], v[84:87], v[98:101], v[12:15]
	v_mfma_f32_16x16x32_bf16 v[8:11], v[84:87], v[204:207], v[8:11]
	v_mfma_f32_16x16x32_bf16 v[4:7], v[92:95], v[98:101], v[4:7]
	v_mfma_f32_16x16x32_bf16 v[0:3], v[92:95], v[204:207], v[0:3]
	v_mfma_f32_16x16x32_bf16 v[134:137], v[72:75], v[200:203], v[28:31]
	v_mfma_f32_16x16x32_bf16 v[146:149], v[72:75], v[160:163], v[24:27]
	v_mfma_f32_16x16x32_bf16 v[152:155], v[80:83], v[200:203], v[20:23]
	v_mfma_f32_16x16x32_bf16 v[192:195], v[80:83], v[160:163], v[16:19]
	v_mfma_f32_16x16x32_bf16 v[226:229], v[88:91], v[200:203], v[12:15]
	v_mfma_f32_16x16x32_bf16 v[230:233], v[88:91], v[160:163], v[8:11]
	v_mfma_f32_16x16x32_bf16 v[200:203], v[188:191], v[200:203], v[4:7]
	v_mfma_f32_16x16x32_bf16 v[160:163], v[188:191], v[160:163], v[0:3]
	s_barrier
	ds_read_b128 v[12:15], v151
	ds_read_b128 v[28:31], v151 offset:1024
	ds_read_b128 v[188:191], v151 offset:2048
	ds_read_b128 v[204:207], v151 offset:3072
	ds_read_b128 v[0:3], v143 offset:32768
	ds_read_b128 v[4:7], v143 offset:33792
	ds_read_b128 v[8:11], v142 offset:32768
	ds_read_b128 v[16:19], v142 offset:33792
	ds_read_b128 v[20:23], v141 offset:32768
	ds_read_b128 v[24:27], v141 offset:33792
	ds_read_b128 v[234:237], v140 offset:32768
	ds_read_b128 v[238:241], v140 offset:33792
	s_waitcnt vmcnt(2)
	s_barrier
	s_waitcnt lgkmcnt(0)
	s_waitcnt lgkmcnt(0)
	v_mfma_f32_16x16x32_bf16 v[68:71], v[0:3], v[12:15], v[126:129]
	v_mfma_f32_16x16x32_bf16 v[72:75], v[8:11], v[12:15], v[118:121]
	v_mfma_f32_16x16x32_bf16 v[76:79], v[20:23], v[12:15], v[110:113]
	v_mfma_f32_16x16x32_bf16 v[80:83], v[234:237], v[12:15], v[102:105]
	v_mfma_f32_16x16x32_bf16 v[84:87], v[4:7], v[28:31], v[68:71]
	v_mfma_f32_16x16x32_bf16 v[68:71], v[0:3], v[188:191], v[122:125]
	v_mfma_f32_16x16x32_bf16 v[88:91], v[16:19], v[28:31], v[72:75]
	v_mfma_f32_16x16x32_bf16 v[72:75], v[8:11], v[188:191], v[114:117]
	v_mfma_f32_16x16x32_bf16 v[92:95], v[24:27], v[28:31], v[76:79]
	v_mfma_f32_16x16x32_bf16 v[76:79], v[20:23], v[188:191], v[106:109]
	v_mfma_f32_16x16x32_bf16 v[98:101], v[238:241], v[28:31], v[80:83]
	v_mfma_f32_16x16x32_bf16 v[80:83], v[234:237], v[188:191], v[196:199]
	v_mfma_f32_16x16x32_bf16 v[68:71], v[4:7], v[204:207], v[68:71]
	v_mfma_f32_16x16x32_bf16 v[72:75], v[16:19], v[204:207], v[72:75]
	v_mfma_f32_16x16x32_bf16 v[76:79], v[24:27], v[204:207], v[76:79]
	v_mfma_f32_16x16x32_bf16 v[80:83], v[238:241], v[204:207], v[80:83]
	s_barrier
	ds_read_b128 v[196:199], v145
	ds_read_b128 v[242:245], v145 offset:1024
	ds_read_b128 v[246:249], v145 offset:2048
	ds_read_b128 v[250:253], v145 offset:3072
	s_waitcnt vmcnt(0)
	s_barrier
	s_waitcnt lgkmcnt(0)
	s_waitcnt lgkmcnt(0)
	v_mfma_f32_16x16x32_bf16 v[102:105], v[0:3], v[196:199], v[222:225]
	v_mfma_f32_16x16x32_bf16 v[0:3], v[0:3], v[246:249], v[156:159]
	v_mfma_f32_16x16x32_bf16 v[118:121], v[4:7], v[242:245], v[102:105]
	v_mfma_f32_16x16x32_bf16 v[102:105], v[4:7], v[250:253], v[0:3]
	v_mfma_f32_16x16x32_bf16 v[0:3], v[8:11], v[196:199], v[164:167]
	v_mfma_f32_16x16x32_bf16 v[122:125], v[16:19], v[242:245], v[0:3]
	v_mfma_f32_16x16x32_bf16 v[0:3], v[8:11], v[246:249], v[168:171]
	v_mfma_f32_16x16x32_bf16 v[106:109], v[16:19], v[250:253], v[0:3]
	v_mfma_f32_16x16x32_bf16 v[0:3], v[20:23], v[196:199], v[176:179]
	v_mfma_f32_16x16x32_bf16 v[126:129], v[24:27], v[242:245], v[0:3]
	v_mfma_f32_16x16x32_bf16 v[0:3], v[20:23], v[246:249], v[180:183]
	v_mfma_f32_16x16x32_bf16 v[110:113], v[24:27], v[250:253], v[0:3]
	v_mfma_f32_16x16x32_bf16 v[0:3], v[234:237], v[196:199], v[184:187]
	v_mfma_f32_16x16x32_bf16 v[130:133], v[238:241], v[242:245], v[0:3]
	v_mfma_f32_16x16x32_bf16 v[0:3], v[234:237], v[246:249], v[64:67]
	v_mfma_f32_16x16x32_bf16 v[114:117], v[238:241], v[250:253], v[0:3]
	s_barrier
	ds_read_b128 v[64:67], v143 offset:49152
	ds_read_b128 v[156:159], v143 offset:50176
	ds_read_b128 v[164:167], v142 offset:49152
	ds_read_b128 v[142:145], v142 offset:50176
	ds_read_b128 v[168:171], v141 offset:49152
	ds_read_b128 v[176:179], v141 offset:50176
	ds_read_b128 v[180:183], v140 offset:49152
	ds_read_b128 v[138:141], v140 offset:50176
	s_barrier
	s_waitcnt lgkmcnt(0)
	s_waitcnt lgkmcnt(0)
	v_mfma_f32_16x16x32_bf16 v[0:3], v[64:67], v[12:15], v[60:63]
	v_mfma_f32_16x16x32_bf16 v[4:7], v[164:167], v[12:15], v[52:55]
	v_mfma_f32_16x16x32_bf16 v[8:11], v[168:171], v[12:15], v[44:47]
	v_mfma_f32_16x16x32_bf16 v[12:15], v[180:183], v[12:15], v[36:39]
	v_mfma_f32_16x16x32_bf16 v[16:19], v[156:159], v[28:31], v[0:3]
	v_mfma_f32_16x16x32_bf16 v[0:3], v[64:67], v[188:191], v[56:59]
	v_mfma_f32_16x16x32_bf16 v[20:23], v[142:145], v[28:31], v[4:7]
	v_mfma_f32_16x16x32_bf16 v[4:7], v[164:167], v[188:191], v[48:51]
	v_mfma_f32_16x16x32_bf16 v[24:27], v[176:179], v[28:31], v[8:11]
	v_mfma_f32_16x16x32_bf16 v[8:11], v[168:171], v[188:191], v[40:43]
	v_mfma_f32_16x16x32_bf16 v[28:31], v[138:141], v[28:31], v[12:15]
	v_mfma_f32_16x16x32_bf16 v[12:15], v[180:183], v[188:191], v[32:35]
	v_mfma_f32_16x16x32_bf16 v[0:3], v[156:159], v[204:207], v[0:3]
	v_mfma_f32_16x16x32_bf16 v[4:7], v[142:145], v[204:207], v[4:7]
	v_mfma_f32_16x16x32_bf16 v[8:11], v[176:179], v[204:207], v[8:11]
	v_mfma_f32_16x16x32_bf16 v[12:15], v[138:141], v[204:207], v[12:15]
	v_mfma_f32_16x16x32_bf16 v[32:35], v[64:67], v[196:199], v[134:137]
	v_mfma_f32_16x16x32_bf16 v[36:39], v[164:167], v[196:199], v[152:155]
	v_mfma_f32_16x16x32_bf16 v[40:43], v[168:171], v[196:199], v[226:229]
	v_mfma_f32_16x16x32_bf16 v[44:47], v[180:183], v[196:199], v[200:203]
	v_mfma_f32_16x16x32_bf16 v[48:51], v[156:159], v[242:245], v[32:35]
	v_mfma_f32_16x16x32_bf16 v[32:35], v[64:67], v[246:249], v[146:149]
	v_mfma_f32_16x16x32_bf16 v[52:55], v[142:145], v[242:245], v[36:39]
	v_mfma_f32_16x16x32_bf16 v[36:39], v[164:167], v[246:249], v[192:195]
	v_mfma_f32_16x16x32_bf16 v[56:59], v[176:179], v[242:245], v[40:43]
	v_mfma_f32_16x16x32_bf16 v[40:43], v[168:171], v[246:249], v[230:233]
	v_mfma_f32_16x16x32_bf16 v[60:63], v[138:141], v[242:245], v[44:47]
	v_mfma_f32_16x16x32_bf16 v[44:47], v[180:183], v[246:249], v[160:163]
	v_mfma_f32_16x16x32_bf16 v[32:35], v[156:159], v[250:253], v[32:35]
	v_mfma_f32_16x16x32_bf16 v[36:39], v[142:145], v[250:253], v[36:39]
	v_mfma_f32_16x16x32_bf16 v[40:43], v[176:179], v[250:253], v[40:43]
	v_mfma_f32_16x16x32_bf16 v[44:47], v[138:141], v[250:253], v[44:47]
	s_movk_i32 s2, 0x100
	v_cmp_gt_u32_e32 vcc, s2, v97
	s_barrier
	s_and_saveexec_b64 s[8:9], vcc
	s_cbranch_execz .LBB0_187
	s_barrier

.LBB0_549:
	ds_read_b128 v[164:167], v161
	ds_read_b128 v[168:171], v161 offset:1024
	ds_read_b128 v[176:179], v161 offset:2048
	ds_read_b128 v[180:183], v161 offset:3072
	v_add_u32_e32 v162, 0xc000, v147
	v_lshl_add_u64 v[172:173], v[134:135], 0, s[12:13]
	v_readfirstlane_b32 s14, v162
	v_add_u32_e32 v163, 0xe000, v147
	v_lshl_add_u64 v[230:231], v[172:173], 0, s[60:61]
	s_mov_b32 m0, s14
	v_lshl_add_u64 v[246:247], v[132:133], 0, s[12:13]
	v_readfirstlane_b32 s14, v163
	ds_read_b128 v[184:187], v143
	ds_read_b128 v[188:191], v143 offset:1024
	ds_read_b128 v[192:195], v142
	ds_read_b128 v[196:199], v142 offset:1024
	ds_read_b128 v[200:203], v141
	ds_read_b128 v[204:207], v141 offset:1024
	ds_read_b128 v[222:225], v140
	ds_read_b128 v[226:229], v140 offset:1024
	global_load_lds_dwordx4 v[230:231], off
	v_lshl_add_u64 v[230:231], v[246:247], 0, s[60:61]
	s_mov_b32 m0, s14
	s_nop 0
	global_load_lds_dwordx4 v[230:231], off
	s_waitcnt lgkmcnt(8)
	s_barrier
	s_waitcnt lgkmcnt(0)
	s_waitcnt lgkmcnt(0)
	v_mfma_f32_16x16x32_bf16 v[126:129], v[184:187], v[164:167], v[126:129]
	v_mfma_f32_16x16x32_bf16 v[122:125], v[184:187], v[176:179], v[122:125]
	v_mfma_f32_16x16x32_bf16 v[118:121], v[192:195], v[164:167], v[118:121]
	v_mfma_f32_16x16x32_bf16 v[114:117], v[192:195], v[176:179], v[114:117]
	v_mfma_f32_16x16x32_bf16 v[110:113], v[200:203], v[164:167], v[110:113]
	v_mfma_f32_16x16x32_bf16 v[106:109], v[200:203], v[176:179], v[106:109]
	v_mfma_f32_16x16x32_bf16 v[102:105], v[222:225], v[164:167], v[102:105]
	v_mfma_f32_16x16x32_bf16 v[98:101], v[222:225], v[176:179], v[98:101]
	v_mfma_f32_16x16x32_bf16 v[126:129], v[188:191], v[168:171], v[126:129]
	v_mfma_f32_16x16x32_bf16 v[122:125], v[188:191], v[180:183], v[122:125]
	v_mfma_f32_16x16x32_bf16 v[118:121], v[196:199], v[168:171], v[118:121]
	v_mfma_f32_16x16x32_bf16 v[114:117], v[196:199], v[180:183], v[114:117]
	v_mfma_f32_16x16x32_bf16 v[110:113], v[204:207], v[168:171], v[110:113]
	v_mfma_f32_16x16x32_bf16 v[106:109], v[204:207], v[180:183], v[106:109]
	v_mfma_f32_16x16x32_bf16 v[102:105], v[226:229], v[168:171], v[102:105]
	v_mfma_f32_16x16x32_bf16 v[98:101], v[226:229], v[180:183], v[98:101]
	s_barrier
	v_lshl_add_u64 v[248:249], v[138:139], 0, s[12:13]
	v_readfirstlane_b32 s14, v144
	v_lshl_add_u64 v[250:251], v[248:249], 0, s[62:63]
	s_mov_b32 m0, s14
	ds_read_b128 v[230:233], v160
	ds_read_b128 v[234:237], v160 offset:1024
	ds_read_b128 v[238:241], v160 offset:2048
	ds_read_b128 v[242:245], v160 offset:3072
	global_load_lds_dwordx4 v[250:251], off
	v_lshl_add_u64 v[250:251], v[136:137], 0, s[12:13]
	v_readfirstlane_b32 s14, v146
	v_lshl_add_u64 v[252:253], v[250:251], 0, s[62:63]
	s_mov_b32 m0, s14
	s_nop 0
	global_load_lds_dwordx4 v[252:253], off
	s_barrier
	s_waitcnt lgkmcnt(0)
	s_waitcnt lgkmcnt(0)
	v_mfma_f32_16x16x32_bf16 v[92:95], v[184:187], v[230:233], v[92:95]
	v_mfma_f32_16x16x32_bf16 v[88:91], v[184:187], v[238:241], v[88:91]
	v_mfma_f32_16x16x32_bf16 v[84:87], v[192:195], v[230:233], v[84:87]
	v_mfma_f32_16x16x32_bf16 v[80:83], v[192:195], v[238:241], v[80:83]
	v_mfma_f32_16x16x32_bf16 v[76:79], v[200:203], v[230:233], v[76:79]
	v_mfma_f32_16x16x32_bf16 v[72:75], v[200:203], v[238:241], v[72:75]
	v_mfma_f32_16x16x32_bf16 v[68:71], v[222:225], v[230:233], v[68:71]
	v_mfma_f32_16x16x32_bf16 v[64:67], v[222:225], v[238:241], v[64:67]
	v_mfma_f32_16x16x32_bf16 v[92:95], v[188:191], v[234:237], v[92:95]
	v_mfma_f32_16x16x32_bf16 v[88:91], v[188:191], v[242:245], v[88:91]
	v_mfma_f32_16x16x32_bf16 v[84:87], v[196:199], v[234:237], v[84:87]
	v_mfma_f32_16x16x32_bf16 v[80:83], v[196:199], v[242:245], v[80:83]
	v_mfma_f32_16x16x32_bf16 v[76:79], v[204:207], v[234:237], v[76:79]
	v_mfma_f32_16x16x32_bf16 v[72:75], v[204:207], v[242:245], v[72:75]
	v_mfma_f32_16x16x32_bf16 v[68:71], v[226:229], v[234:237], v[68:71]
	v_mfma_f32_16x16x32_bf16 v[64:67], v[226:229], v[242:245], v[64:67]
	v_readfirstlane_b32 s14, v147
	v_lshl_add_u64 v[252:253], v[172:173], 0, s[62:63]
	s_mov_b32 m0, s14
	v_readfirstlane_b32 s14, v148
	s_barrier
	ds_read_b128 v[184:187], v143 offset:16384
	ds_read_b128 v[188:191], v143 offset:17408
	ds_read_b128 v[192:195], v142 offset:16384
	ds_read_b128 v[196:199], v142 offset:17408
	ds_read_b128 v[200:203], v141 offset:16384
	ds_read_b128 v[204:207], v141 offset:17408
	ds_read_b128 v[222:225], v140 offset:16384
	ds_read_b128 v[226:229], v140 offset:17408
	global_load_lds_dwordx4 v[252:253], off
	v_lshl_add_u64 v[252:253], v[246:247], 0, s[62:63]
	s_mov_b32 m0, s14
	s_nop 0
	global_load_lds_dwordx4 v[252:253], off
	s_barrier
	s_waitcnt lgkmcnt(0)
	s_waitcnt lgkmcnt(0)
	v_mfma_f32_16x16x32_bf16 v[60:63], v[184:187], v[164:167], v[60:63]
	v_mfma_f32_16x16x32_bf16 v[56:59], v[184:187], v[176:179], v[56:59]
	v_mfma_f32_16x16x32_bf16 v[52:55], v[192:195], v[164:167], v[52:55]
	v_mfma_f32_16x16x32_bf16 v[48:51], v[192:195], v[176:179], v[48:51]
	v_mfma_f32_16x16x32_bf16 v[44:47], v[200:203], v[164:167], v[44:47]
	v_mfma_f32_16x16x32_bf16 v[40:43], v[200:203], v[176:179], v[40:43]
	v_mfma_f32_16x16x32_bf16 v[36:39], v[222:225], v[164:167], v[36:39]
	v_mfma_f32_16x16x32_bf16 v[32:35], v[222:225], v[176:179], v[32:35]
	v_mfma_f32_16x16x32_bf16 v[60:63], v[188:191], v[168:171], v[60:63]
	v_mfma_f32_16x16x32_bf16 v[56:59], v[188:191], v[180:183], v[56:59]
	v_mfma_f32_16x16x32_bf16 v[52:55], v[196:199], v[168:171], v[52:55]
	v_mfma_f32_16x16x32_bf16 v[48:51], v[196:199], v[180:183], v[48:51]
	v_mfma_f32_16x16x32_bf16 v[44:47], v[204:207], v[168:171], v[44:47]
	v_mfma_f32_16x16x32_bf16 v[40:43], v[204:207], v[180:183], v[40:43]
	v_mfma_f32_16x16x32_bf16 v[36:39], v[226:229], v[168:171], v[36:39]
	v_mfma_f32_16x16x32_bf16 v[32:35], v[226:229], v[180:183], v[32:35]
	s_barrier
	v_readfirstlane_b32 s14, v149
	v_lshl_add_u64 v[164:165], v[248:249], 0, s[64:65]
	s_mov_b32 m0, s14
	v_readfirstlane_b32 s14, v150
	global_load_lds_dwordx4 v[164:165], off
	v_lshl_add_u64 v[164:165], v[250:251], 0, s[64:65]
	s_mov_b32 m0, s14
	s_nop 0
	global_load_lds_dwordx4 v[164:165], off
	s_waitcnt vmcnt(6)
	s_barrier
	v_mfma_f32_16x16x32_bf16 v[28:31], v[184:187], v[230:233], v[28:31]
	v_mfma_f32_16x16x32_bf16 v[24:27], v[184:187], v[238:241], v[24:27]
	v_mfma_f32_16x16x32_bf16 v[20:23], v[192:195], v[230:233], v[20:23]
	v_mfma_f32_16x16x32_bf16 v[16:19], v[192:195], v[238:241], v[16:19]
	v_mfma_f32_16x16x32_bf16 v[12:15], v[200:203], v[230:233], v[12:15]
	v_mfma_f32_16x16x32_bf16 v[8:11], v[200:203], v[238:241], v[8:11]
	v_mfma_f32_16x16x32_bf16 v[4:7], v[222:225], v[230:233], v[4:7]
	v_mfma_f32_16x16x32_bf16 v[0:3], v[222:225], v[238:241], v[0:3]
	v_mfma_f32_16x16x32_bf16 v[28:31], v[188:191], v[234:237], v[28:31]
	v_mfma_f32_16x16x32_bf16 v[24:27], v[188:191], v[242:245], v[24:27]
	v_mfma_f32_16x16x32_bf16 v[20:23], v[196:199], v[234:237], v[20:23]
	v_mfma_f32_16x16x32_bf16 v[16:19], v[196:199], v[242:245], v[16:19]
	v_mfma_f32_16x16x32_bf16 v[12:15], v[204:207], v[234:237], v[12:15]
	v_mfma_f32_16x16x32_bf16 v[8:11], v[204:207], v[242:245], v[8:11]
	v_mfma_f32_16x16x32_bf16 v[4:7], v[226:229], v[234:237], v[4:7]
	v_mfma_f32_16x16x32_bf16 v[0:3], v[226:229], v[242:245], v[0:3]
	s_barrier
	ds_read_b128 v[164:167], v151
	ds_read_b128 v[168:171], v151 offset:1024
	ds_read_b128 v[176:179], v151 offset:2048
	ds_read_b128 v[180:183], v151 offset:3072
	v_readfirstlane_b32 s14, v152
	v_lshl_add_u64 v[230:231], v[172:173], 0, s[64:65]
	s_mov_b32 m0, s14
	v_readfirstlane_b32 s14, v153
	ds_read_b128 v[184:187], v143 offset:32768
	ds_read_b128 v[188:191], v143 offset:33792
	ds_read_b128 v[192:195], v142 offset:32768
	ds_read_b128 v[196:199], v142 offset:33792
	ds_read_b128 v[200:203], v141 offset:32768
	ds_read_b128 v[204:207], v141 offset:33792
	ds_read_b128 v[222:225], v140 offset:32768
	ds_read_b128 v[226:229], v140 offset:33792
	global_load_lds_dwordx4 v[230:231], off
	v_lshl_add_u64 v[230:231], v[246:247], 0, s[64:65]
	s_mov_b32 m0, s14
	s_nop 0
	global_load_lds_dwordx4 v[230:231], off
	s_waitcnt lgkmcnt(8)
	s_barrier
	s_waitcnt lgkmcnt(0)
	s_waitcnt lgkmcnt(0)
	v_mfma_f32_16x16x32_bf16 v[126:129], v[184:187], v[164:167], v[126:129]
	v_mfma_f32_16x16x32_bf16 v[122:125], v[184:187], v[176:179], v[122:125]
	v_mfma_f32_16x16x32_bf16 v[118:121], v[192:195], v[164:167], v[118:121]
	v_mfma_f32_16x16x32_bf16 v[114:117], v[192:195], v[176:179], v[114:117]
	v_mfma_f32_16x16x32_bf16 v[110:113], v[200:203], v[164:167], v[110:113]
	v_mfma_f32_16x16x32_bf16 v[106:109], v[200:203], v[176:179], v[106:109]
	v_mfma_f32_16x16x32_bf16 v[102:105], v[222:225], v[164:167], v[102:105]
	v_mfma_f32_16x16x32_bf16 v[98:101], v[222:225], v[176:179], v[98:101]
	v_mfma_f32_16x16x32_bf16 v[126:129], v[188:191], v[168:171], v[126:129]
	v_mfma_f32_16x16x32_bf16 v[122:125], v[188:191], v[180:183], v[122:125]
	v_mfma_f32_16x16x32_bf16 v[118:121], v[196:199], v[168:171], v[118:121]
	v_mfma_f32_16x16x32_bf16 v[114:117], v[196:199], v[180:183], v[114:117]
	v_mfma_f32_16x16x32_bf16 v[110:113], v[204:207], v[168:171], v[110:113]
	v_mfma_f32_16x16x32_bf16 v[106:109], v[204:207], v[180:183], v[106:109]
	v_mfma_f32_16x16x32_bf16 v[102:105], v[226:229], v[168:171], v[102:105]
	v_mfma_f32_16x16x32_bf16 v[98:101], v[226:229], v[180:183], v[98:101]
	s_barrier
	v_readfirstlane_b32 s14, v154
	v_lshl_add_u64 v[252:253], v[248:249], 0, s[66:67]
	s_mov_b32 m0, s14
	v_readfirstlane_b32 s14, v155
	ds_read_b128 v[230:233], v145
	ds_read_b128 v[234:237], v145 offset:1024
	ds_read_b128 v[238:241], v145 offset:2048
	ds_read_b128 v[242:245], v145 offset:3072
	global_load_lds_dwordx4 v[252:253], off
	v_lshl_add_u64 v[252:253], v[250:251], 0, s[66:67]
	s_mov_b32 m0, s14
	s_nop 0
	global_load_lds_dwordx4 v[252:253], off
	s_barrier
	s_waitcnt lgkmcnt(0)
	s_waitcnt lgkmcnt(0)
	v_mfma_f32_16x16x32_bf16 v[92:95], v[184:187], v[230:233], v[92:95]
	v_mfma_f32_16x16x32_bf16 v[88:91], v[184:187], v[238:241], v[88:91]
	v_mfma_f32_16x16x32_bf16 v[84:87], v[192:195], v[230:233], v[84:87]
	v_mfma_f32_16x16x32_bf16 v[80:83], v[192:195], v[238:241], v[80:83]
	v_mfma_f32_16x16x32_bf16 v[76:79], v[200:203], v[230:233], v[76:79]
	v_mfma_f32_16x16x32_bf16 v[72:75], v[200:203], v[238:241], v[72:75]
	v_mfma_f32_16x16x32_bf16 v[68:71], v[222:225], v[230:233], v[68:71]
	v_mfma_f32_16x16x32_bf16 v[64:67], v[222:225], v[238:241], v[64:67]
	v_mfma_f32_16x16x32_bf16 v[92:95], v[188:191], v[234:237], v[92:95]
	v_mfma_f32_16x16x32_bf16 v[88:91], v[188:191], v[242:245], v[88:91]
	v_mfma_f32_16x16x32_bf16 v[84:87], v[196:199], v[234:237], v[84:87]
	v_mfma_f32_16x16x32_bf16 v[80:83], v[196:199], v[242:245], v[80:83]
	v_mfma_f32_16x16x32_bf16 v[76:79], v[204:207], v[234:237], v[76:79]
	v_mfma_f32_16x16x32_bf16 v[72:75], v[204:207], v[242:245], v[72:75]
	v_mfma_f32_16x16x32_bf16 v[68:71], v[226:229], v[234:237], v[68:71]
	v_mfma_f32_16x16x32_bf16 v[64:67], v[226:229], v[242:245], v[64:67]
	v_readfirstlane_b32 s14, v156
	v_lshl_add_u64 v[172:173], v[172:173], 0, s[66:67]
	s_mov_b32 m0, s14
	v_readfirstlane_b32 s14, v157
	s_barrier
	ds_read_b128 v[184:187], v143 offset:49152
	ds_read_b128 v[188:191], v143 offset:50176
	ds_read_b128 v[192:195], v142 offset:49152
	ds_read_b128 v[196:199], v142 offset:50176
	ds_read_b128 v[200:203], v141 offset:49152
	ds_read_b128 v[204:207], v141 offset:50176
	ds_read_b128 v[222:225], v140 offset:49152
	ds_read_b128 v[226:229], v140 offset:50176
	global_load_lds_dwordx4 v[172:173], off
	v_lshl_add_u64 v[172:173], v[246:247], 0, s[66:67]
	s_mov_b32 m0, s14
	s_nop 0
	global_load_lds_dwordx4 v[172:173], off
	s_barrier
	s_waitcnt lgkmcnt(0)
	s_waitcnt lgkmcnt(0)
	v_mfma_f32_16x16x32_bf16 v[60:63], v[184:187], v[164:167], v[60:63]
	v_mfma_f32_16x16x32_bf16 v[56:59], v[184:187], v[176:179], v[56:59]
	v_mfma_f32_16x16x32_bf16 v[52:55], v[192:195], v[164:167], v[52:55]
	v_mfma_f32_16x16x32_bf16 v[48:51], v[192:195], v[176:179], v[48:51]
	v_mfma_f32_16x16x32_bf16 v[44:47], v[200:203], v[164:167], v[44:47]
	v_mfma_f32_16x16x32_bf16 v[40:43], v[200:203], v[176:179], v[40:43]
	v_mfma_f32_16x16x32_bf16 v[36:39], v[222:225], v[164:167], v[36:39]
	v_mfma_f32_16x16x32_bf16 v[32:35], v[222:225], v[176:179], v[32:35]
	v_mfma_f32_16x16x32_bf16 v[60:63], v[188:191], v[168:171], v[60:63]
	v_mfma_f32_16x16x32_bf16 v[56:59], v[188:191], v[180:183], v[56:59]
	v_mfma_f32_16x16x32_bf16 v[52:55], v[196:199], v[168:171], v[52:55]
	v_mfma_f32_16x16x32_bf16 v[48:51], v[196:199], v[180:183], v[48:51]
	v_mfma_f32_16x16x32_bf16 v[44:47], v[204:207], v[168:171], v[44:47]
	v_mfma_f32_16x16x32_bf16 v[40:43], v[204:207], v[180:183], v[40:43]
	v_mfma_f32_16x16x32_bf16 v[36:39], v[226:229], v[168:171], v[36:39]
	v_mfma_f32_16x16x32_bf16 v[32:35], v[226:229], v[180:183], v[32:35]
	s_barrier
	v_readfirstlane_b32 s14, v158
	v_lshl_add_u64 v[164:165], v[248:249], 0, s[68:69]
	s_mov_b32 m0, s14
	v_readfirstlane_b32 s14, v159
	global_load_lds_dwordx4 v[164:165], off
	v_lshl_add_u64 v[164:165], v[250:251], 0, s[68:69]
	s_mov_b32 m0, s14
	s_nop 0
	global_load_lds_dwordx4 v[164:165], off
	s_waitcnt vmcnt(6)
	s_barrier
	v_mfma_f32_16x16x32_bf16 v[28:31], v[184:187], v[230:233], v[28:31]
	v_mfma_f32_16x16x32_bf16 v[24:27], v[184:187], v[238:241], v[24:27]
	v_mfma_f32_16x16x32_bf16 v[20:23], v[192:195], v[230:233], v[20:23]
	v_mfma_f32_16x16x32_bf16 v[16:19], v[192:195], v[238:241], v[16:19]
	v_mfma_f32_16x16x32_bf16 v[12:15], v[200:203], v[230:233], v[12:15]
	v_mfma_f32_16x16x32_bf16 v[8:11], v[200:203], v[238:241], v[8:11]
	v_mfma_f32_16x16x32_bf16 v[4:7], v[222:225], v[230:233], v[4:7]
	v_mfma_f32_16x16x32_bf16 v[0:3], v[222:225], v[238:241], v[0:3]
	v_mfma_f32_16x16x32_bf16 v[28:31], v[188:191], v[234:237], v[28:31]
	v_mfma_f32_16x16x32_bf16 v[24:27], v[188:191], v[242:245], v[24:27]
	v_mfma_f32_16x16x32_bf16 v[20:23], v[196:199], v[234:237], v[20:23]
	v_mfma_f32_16x16x32_bf16 v[16:19], v[196:199], v[242:245], v[16:19]
	v_mfma_f32_16x16x32_bf16 v[12:15], v[204:207], v[234:237], v[12:15]
	v_mfma_f32_16x16x32_bf16 v[8:11], v[204:207], v[242:245], v[8:11]
	v_mfma_f32_16x16x32_bf16 v[4:7], v[226:229], v[234:237], v[4:7]
	v_mfma_f32_16x16x32_bf16 v[0:3], v[226:229], v[242:245], v[0:3]
	s_add_i32 s9, s9, 2
	s_add_u32 s12, s12, 0x100
	s_addc_u32 s13, s13, 0
	s_cmp_lt_u32 s9, 28
	s_barrier
	s_cbranch_scc1 .LBB0_549
	s_add_u32 s10, s10, 0x80f80
	s_addc_u32 s11, s11, 0
	v_readfirstlane_b32 s9, v162
	v_lshl_add_u64 v[172:173], s[10:11], 0, v[174:175]
	s_mov_b32 m0, s9
	v_readfirstlane_b32 s9, v163
	ds_read_b128 v[132:135], v161
	ds_read_b128 v[136:139], v161 offset:1024
	ds_read_b128 v[146:149], v161 offset:2048
	ds_read_b128 v[152:155], v161 offset:3072
	ds_read_b128 v[156:159], v143
	ds_read_b128 v[164:167], v143 offset:1024
	ds_read_b128 v[168:171], v142
	ds_read_b128 v[176:179], v142 offset:1024
	ds_read_b128 v[180:183], v141
	ds_read_b128 v[184:187], v141 offset:1024
	ds_read_b128 v[188:191], v140
	ds_read_b128 v[192:195], v140 offset:1024
	global_load_lds_dwordx4 v[172:173], off
	v_lshl_add_u64 v[130:131], s[10:11], 0, v[130:131]
	s_mov_b32 m0, s9
	s_nop 0
	global_load_lds_dwordx4 v[130:131], off
	s_barrier
	s_waitcnt lgkmcnt(0)
	s_waitcnt lgkmcnt(0)
	v_mfma_f32_16x16x32_bf16 v[126:129], v[156:159], v[132:135], v[126:129]
	v_mfma_f32_16x16x32_bf16 v[122:125], v[156:159], v[146:149], v[122:125]
	v_mfma_f32_16x16x32_bf16 v[118:121], v[168:171], v[132:135], v[118:121]
	v_mfma_f32_16x16x32_bf16 v[114:117], v[168:171], v[146:149], v[114:117]
	v_mfma_f32_16x16x32_bf16 v[110:113], v[180:183], v[132:135], v[110:113]
	v_mfma_f32_16x16x32_bf16 v[106:109], v[180:183], v[146:149], v[106:109]
	v_mfma_f32_16x16x32_bf16 v[102:105], v[188:191], v[132:135], v[102:105]
	v_mfma_f32_16x16x32_bf16 v[98:101], v[188:191], v[146:149], v[98:101]
	v_mfma_f32_16x16x32_bf16 v[126:129], v[164:167], v[136:139], v[126:129]
	v_mfma_f32_16x16x32_bf16 v[122:125], v[164:167], v[152:155], v[122:125]
	v_mfma_f32_16x16x32_bf16 v[118:121], v[176:179], v[136:139], v[118:121]
	v_mfma_f32_16x16x32_bf16 v[114:117], v[176:179], v[152:155], v[114:117]
	v_mfma_f32_16x16x32_bf16 v[110:113], v[184:187], v[136:139], v[110:113]
	v_mfma_f32_16x16x32_bf16 v[106:109], v[184:187], v[152:155], v[106:109]
	v_mfma_f32_16x16x32_bf16 v[102:105], v[192:195], v[136:139], v[102:105]
	v_mfma_f32_16x16x32_bf16 v[98:101], v[192:195], v[152:155], v[98:101]
	s_barrier
	ds_read_b128 v[196:199], v160
	ds_read_b128 v[200:203], v160 offset:1024
	ds_read_b128 v[204:207], v160 offset:2048
	ds_read_b128 v[160:163], v160 offset:3072
	s_barrier
	s_waitcnt lgkmcnt(0)
	s_waitcnt lgkmcnt(0)
	v_mfma_f32_16x16x32_bf16 v[92:95], v[156:159], v[196:199], v[92:95]
	v_mfma_f32_16x16x32_bf16 v[88:91], v[156:159], v[204:207], v[88:91]
	v_mfma_f32_16x16x32_bf16 v[84:87], v[168:171], v[196:199], v[84:87]
	v_mfma_f32_16x16x32_bf16 v[80:83], v[168:171], v[204:207], v[80:83]
	v_mfma_f32_16x16x32_bf16 v[76:79], v[180:183], v[196:199], v[76:79]
	v_mfma_f32_16x16x32_bf16 v[72:75], v[180:183], v[204:207], v[72:75]
	v_mfma_f32_16x16x32_bf16 v[68:71], v[188:191], v[196:199], v[68:71]
	v_mfma_f32_16x16x32_bf16 v[64:67], v[188:191], v[204:207], v[64:67]
	v_mfma_f32_16x16x32_bf16 v[222:225], v[164:167], v[200:203], v[92:95]
	v_mfma_f32_16x16x32_bf16 v[156:159], v[164:167], v[160:163], v[88:91]
	v_mfma_f32_16x16x32_bf16 v[164:167], v[176:179], v[200:203], v[84:87]
	v_mfma_f32_16x16x32_bf16 v[168:171], v[176:179], v[160:163], v[80:83]
	v_mfma_f32_16x16x32_bf16 v[176:179], v[184:187], v[200:203], v[76:79]
	v_mfma_f32_16x16x32_bf16 v[180:183], v[184:187], v[160:163], v[72:75]
	v_mfma_f32_16x16x32_bf16 v[184:187], v[192:195], v[200:203], v[68:71]
	v_mfma_f32_16x16x32_bf16 v[188:191], v[192:195], v[160:163], v[64:67]
	s_barrier
	s_nop 0
	ds_read_b128 v[64:67], v143 offset:16384
	ds_read_b128 v[68:71], v143 offset:17408
	ds_read_b128 v[72:75], v142 offset:16384
	ds_read_b128 v[76:79], v142 offset:17408
	ds_read_b128 v[80:83], v141 offset:16384
	ds_read_b128 v[84:87], v141 offset:17408
	ds_read_b128 v[88:91], v140 offset:16384
	ds_read_b128 v[92:95], v140 offset:17408
	s_waitcnt vmcnt(4)
	s_barrier
	s_waitcnt lgkmcnt(0)
	s_waitcnt lgkmcnt(0)
	v_mfma_f32_16x16x32_bf16 v[60:63], v[64:67], v[132:135], v[60:63]
	v_mfma_f32_16x16x32_bf16 v[56:59], v[64:67], v[146:149], v[56:59]
	v_mfma_f32_16x16x32_bf16 v[52:55], v[72:75], v[132:135], v[52:55]
	v_mfma_f32_16x16x32_bf16 v[48:51], v[72:75], v[146:149], v[48:51]
	v_mfma_f32_16x16x32_bf16 v[44:47], v[80:83], v[132:135], v[44:47]
	v_mfma_f32_16x16x32_bf16 v[40:43], v[80:83], v[146:149], v[40:43]
	v_mfma_f32_16x16x32_bf16 v[36:39], v[88:91], v[132:135], v[36:39]
	v_mfma_f32_16x16x32_bf16 v[32:35], v[88:91], v[146:149], v[32:35]
	v_mfma_f32_16x16x32_bf16 v[60:63], v[68:71], v[136:139], v[60:63]
	v_mfma_f32_16x16x32_bf16 v[56:59], v[68:71], v[152:155], v[56:59]
	v_mfma_f32_16x16x32_bf16 v[52:55], v[76:79], v[136:139], v[52:55]
	v_mfma_f32_16x16x32_bf16 v[48:51], v[76:79], v[152:155], v[48:51]
	v_mfma_f32_16x16x32_bf16 v[44:47], v[84:87], v[136:139], v[44:47]
	v_mfma_f32_16x16x32_bf16 v[40:43], v[84:87], v[152:155], v[40:43]
	v_mfma_f32_16x16x32_bf16 v[36:39], v[92:95], v[136:139], v[36:39]
	v_mfma_f32_16x16x32_bf16 v[32:35], v[92:95], v[152:155], v[32:35]
	v_mfma_f32_16x16x32_bf16 v[28:31], v[64:67], v[196:199], v[28:31]
	v_mfma_f32_16x16x32_bf16 v[24:27], v[64:67], v[204:207], v[24:27]
	v_mfma_f32_16x16x32_bf16 v[20:23], v[72:75], v[196:199], v[20:23]
	v_mfma_f32_16x16x32_bf16 v[16:19], v[72:75], v[204:207], v[16:19]
	v_mfma_f32_16x16x32_bf16 v[12:15], v[80:83], v[196:199], v[12:15]
	v_mfma_f32_16x16x32_bf16 v[8:11], v[80:83], v[204:207], v[8:11]
	v_mfma_f32_16x16x32_bf16 v[4:7], v[88:91], v[196:199], v[4:7]
	v_mfma_f32_16x16x32_bf16 v[0:3], v[88:91], v[204:207], v[0:3]
	v_mfma_f32_16x16x32_bf16 v[130:133], v[68:71], v[200:203], v[28:31]
	v_mfma_f32_16x16x32_bf16 v[134:137], v[68:71], v[160:163], v[24:27]
	v_mfma_f32_16x16x32_bf16 v[146:149], v[76:79], v[200:203], v[20:23]
	v_mfma_f32_16x16x32_bf16 v[152:155], v[76:79], v[160:163], v[16:19]
	v_mfma_f32_16x16x32_bf16 v[192:195], v[84:87], v[200:203], v[12:15]
	v_mfma_f32_16x16x32_bf16 v[226:229], v[84:87], v[160:163], v[8:11]
	v_mfma_f32_16x16x32_bf16 v[196:199], v[92:95], v[200:203], v[4:7]
	v_mfma_f32_16x16x32_bf16 v[160:163], v[92:95], v[160:163], v[0:3]
	s_barrier
	ds_read_b128 v[12:15], v151
	ds_read_b128 v[28:31], v151 offset:1024
	ds_read_b128 v[200:203], v151 offset:2048
	ds_read_b128 v[204:207], v151 offset:3072
	ds_read_b128 v[0:3], v143 offset:32768
	ds_read_b128 v[4:7], v143 offset:33792
	ds_read_b128 v[8:11], v142 offset:32768
	ds_read_b128 v[16:19], v142 offset:33792
	ds_read_b128 v[20:23], v141 offset:32768
	ds_read_b128 v[24:27], v141 offset:33792
	ds_read_b128 v[230:233], v140 offset:32768
	ds_read_b128 v[234:237], v140 offset:33792
	s_waitcnt vmcnt(2)
	s_barrier
	s_waitcnt lgkmcnt(0)
	s_waitcnt lgkmcnt(0)
	v_mfma_f32_16x16x32_bf16 v[64:67], v[0:3], v[12:15], v[126:129]
	v_mfma_f32_16x16x32_bf16 v[68:71], v[8:11], v[12:15], v[118:121]
	v_mfma_f32_16x16x32_bf16 v[72:75], v[20:23], v[12:15], v[110:113]
	v_mfma_f32_16x16x32_bf16 v[76:79], v[230:233], v[12:15], v[102:105]
	v_mfma_f32_16x16x32_bf16 v[80:83], v[4:7], v[28:31], v[64:67]
	v_mfma_f32_16x16x32_bf16 v[64:67], v[0:3], v[200:203], v[122:125]
	v_mfma_f32_16x16x32_bf16 v[84:87], v[16:19], v[28:31], v[68:71]
	v_mfma_f32_16x16x32_bf16 v[68:71], v[8:11], v[200:203], v[114:117]
	v_mfma_f32_16x16x32_bf16 v[88:91], v[24:27], v[28:31], v[72:75]
	v_mfma_f32_16x16x32_bf16 v[72:75], v[20:23], v[200:203], v[106:109]
	v_mfma_f32_16x16x32_bf16 v[92:95], v[234:237], v[28:31], v[76:79]
	v_mfma_f32_16x16x32_bf16 v[76:79], v[230:233], v[200:203], v[98:101]
	v_mfma_f32_16x16x32_bf16 v[64:67], v[4:7], v[204:207], v[64:67]
	v_mfma_f32_16x16x32_bf16 v[68:71], v[16:19], v[204:207], v[68:71]
	v_mfma_f32_16x16x32_bf16 v[72:75], v[24:27], v[204:207], v[72:75]
	v_mfma_f32_16x16x32_bf16 v[76:79], v[234:237], v[204:207], v[76:79]
	s_barrier
	ds_read_b128 v[238:241], v145
	ds_read_b128 v[242:245], v145 offset:1024
	ds_read_b128 v[246:249], v145 offset:2048
	ds_read_b128 v[250:253], v145 offset:3072
	s_waitcnt vmcnt(0)
	s_barrier
	s_waitcnt lgkmcnt(0)
	s_waitcnt lgkmcnt(0)
	v_mfma_f32_16x16x32_bf16 v[98:101], v[0:3], v[238:241], v[222:225]
	v_mfma_f32_16x16x32_bf16 v[0:3], v[0:3], v[246:249], v[156:159]
	v_mfma_f32_16x16x32_bf16 v[114:117], v[4:7], v[242:245], v[98:101]
	v_mfma_f32_16x16x32_bf16 v[98:101], v[4:7], v[250:253], v[0:3]
	v_mfma_f32_16x16x32_bf16 v[0:3], v[8:11], v[238:241], v[164:167]
	v_mfma_f32_16x16x32_bf16 v[118:121], v[16:19], v[242:245], v[0:3]
	v_mfma_f32_16x16x32_bf16 v[0:3], v[8:11], v[246:249], v[168:171]
	v_mfma_f32_16x16x32_bf16 v[102:105], v[16:19], v[250:253], v[0:3]
	v_mfma_f32_16x16x32_bf16 v[0:3], v[20:23], v[238:241], v[176:179]
	v_mfma_f32_16x16x32_bf16 v[122:125], v[24:27], v[242:245], v[0:3]
	v_mfma_f32_16x16x32_bf16 v[0:3], v[20:23], v[246:249], v[180:183]
	v_mfma_f32_16x16x32_bf16 v[106:109], v[24:27], v[250:253], v[0:3]
	v_mfma_f32_16x16x32_bf16 v[0:3], v[230:233], v[238:241], v[184:187]
	v_mfma_f32_16x16x32_bf16 v[126:129], v[234:237], v[242:245], v[0:3]
	v_mfma_f32_16x16x32_bf16 v[0:3], v[230:233], v[246:249], v[188:191]
	v_mfma_f32_16x16x32_bf16 v[110:113], v[234:237], v[250:253], v[0:3]
	s_barrier
	ds_read_b128 v[156:159], v143 offset:49152
	ds_read_b128 v[164:167], v143 offset:50176
	ds_read_b128 v[168:171], v142 offset:49152
	ds_read_b128 v[142:145], v142 offset:50176
	ds_read_b128 v[176:179], v141 offset:49152
	ds_read_b128 v[180:183], v141 offset:50176
	ds_read_b128 v[184:187], v140 offset:49152
	ds_read_b128 v[138:141], v140 offset:50176
	s_barrier
	s_waitcnt lgkmcnt(0)
	s_waitcnt lgkmcnt(0)
	v_mfma_f32_16x16x32_bf16 v[0:3], v[156:159], v[12:15], v[60:63]
	v_mfma_f32_16x16x32_bf16 v[4:7], v[168:171], v[12:15], v[52:55]
	v_mfma_f32_16x16x32_bf16 v[8:11], v[176:179], v[12:15], v[44:47]
	v_mfma_f32_16x16x32_bf16 v[12:15], v[184:187], v[12:15], v[36:39]
	v_mfma_f32_16x16x32_bf16 v[16:19], v[164:167], v[28:31], v[0:3]
	v_mfma_f32_16x16x32_bf16 v[0:3], v[156:159], v[200:203], v[56:59]
	v_mfma_f32_16x16x32_bf16 v[20:23], v[142:145], v[28:31], v[4:7]
	v_mfma_f32_16x16x32_bf16 v[4:7], v[168:171], v[200:203], v[48:51]
	v_mfma_f32_16x16x32_bf16 v[24:27], v[180:183], v[28:31], v[8:11]
	v_mfma_f32_16x16x32_bf16 v[8:11], v[176:179], v[200:203], v[40:43]
	v_mfma_f32_16x16x32_bf16 v[28:31], v[138:141], v[28:31], v[12:15]
	v_mfma_f32_16x16x32_bf16 v[12:15], v[184:187], v[200:203], v[32:35]
	v_mfma_f32_16x16x32_bf16 v[0:3], v[164:167], v[204:207], v[0:3]
	v_mfma_f32_16x16x32_bf16 v[4:7], v[142:145], v[204:207], v[4:7]
	v_mfma_f32_16x16x32_bf16 v[8:11], v[180:183], v[204:207], v[8:11]
	v_mfma_f32_16x16x32_bf16 v[12:15], v[138:141], v[204:207], v[12:15]
	v_mfma_f32_16x16x32_bf16 v[32:35], v[156:159], v[238:241], v[130:133]
	v_mfma_f32_16x16x32_bf16 v[36:39], v[168:171], v[238:241], v[146:149]
	v_mfma_f32_16x16x32_bf16 v[40:43], v[176:179], v[238:241], v[192:195]
	v_mfma_f32_16x16x32_bf16 v[44:47], v[184:187], v[238:241], v[196:199]
	v_mfma_f32_16x16x32_bf16 v[48:51], v[164:167], v[242:245], v[32:35]
	v_mfma_f32_16x16x32_bf16 v[32:35], v[156:159], v[246:249], v[134:137]
	v_mfma_f32_16x16x32_bf16 v[52:55], v[142:145], v[242:245], v[36:39]
	v_mfma_f32_16x16x32_bf16 v[36:39], v[168:171], v[246:249], v[152:155]
	v_mfma_f32_16x16x32_bf16 v[56:59], v[180:183], v[242:245], v[40:43]
	v_mfma_f32_16x16x32_bf16 v[40:43], v[176:179], v[246:249], v[226:229]
	v_mfma_f32_16x16x32_bf16 v[60:63], v[138:141], v[242:245], v[44:47]
	v_mfma_f32_16x16x32_bf16 v[44:47], v[184:187], v[246:249], v[160:163]
	v_mfma_f32_16x16x32_bf16 v[32:35], v[164:167], v[250:253], v[32:35]
	v_mfma_f32_16x16x32_bf16 v[36:39], v[142:145], v[250:253], v[36:39]
	v_mfma_f32_16x16x32_bf16 v[40:43], v[180:183], v[250:253], v[40:43]
	v_mfma_f32_16x16x32_bf16 v[44:47], v[138:141], v[250:253], v[44:47]
	s_movk_i32 s9, 0x100
	v_cmp_gt_u32_e32 vcc, s9, v97
	s_barrier
	s_and_saveexec_b64 s[10:11], vcc
	s_cbranch_execz .LBB0_552
	s_barrier
